# ADIFF fast loop: slot-delta / K-base update and chunk ch+3 DMA address math moved in front of the per-chunk barrier, common vmcnt(4) path falls through (vmcnt(0) case out of line): no scalar work betw
# speedup vs baseline: 1.0140x; 1.0140x over previous
; #define LAS __attribute__((address_space(3)))
; __device__ __forceinline__ void diff_attn_phase(const Params& p, LAS unsigned char* lds) {
;     ...
;         for (int ch = 0; ch < NCH; ++ch) {
;             if (ch + 1 < NCH) asm volatile("s_waitcnt vmcnt(4)" ::: "memory"); else asm volatile("s_waitcnt vmcnt(0)" ::: "memory");
;             __builtin_amdgcn_s_barrier(); asm volatile("" ::: "memory");
;             if (ch + 2 < NCH) issue(ch + 2, s_nn);
;             const LAS unsigned char* Ksb = lds + s_cur * STG; const LAS unsigned char* Vsb = Ksb + 16384;
;             s_nn = s_cur; s_cur = (s_cur == 2) ? 0 : s_cur + 1;
; #pragma clang loop unroll(disable)
;             for (int u = 0; u < 2; ++u) {
;                 const LAS unsigned char* Ku = Ksb + u * 8192; const LAS unsigned char* Vu = Vsb + u * 8192;
;                 int kxl = kx, vb0l = vb0, vb1l = vb1; asm volatile("" : "+v"(kxl), "+v"(vb0l), "+v"(vb1l));
;                 bf16x8 kf[4];
; #pragma unroll
;                 for (int ks = 0; ks < 4; ++ks) kf[ks] = *(const LAS bf16x8*)(Ku + kbase + (kxl ^ (32 * ks)));
;                 bf16x8 P[2][2];
; #pragma unroll
;                 for (int r = 0; r < 2; ++r) {
;                     f32x16 S;
; #pragma unroll
;                     for (int i = 0; i < 16; ++i) S[i] = 0.f;
; #pragma unroll
;                     for (int ks = 0; ks < 4; ++ks) S = __builtin_amdgcn_mfma_f32_32x32x16_bf16(kf[ks], qf[r][ks], S, 0, 0, 0);
;                     S = __builtin_amdgcn_mfma_f32_32x32x16_bf16(kone, qm[r], S, 0, 0, 0);
; #pragma unroll
;                     for (int i = 0; i < 16; ++i) S[i] = __builtin_amdgcn_exp2f(S[i]);
;                     l[r] += sum16(S);
;                     P[r][0] = pack8(S, 0); P[r][1] = pack8(S, 8);
;                 }
; #pragma unroll
;                 for (int t = 0; t < 4; ++t) {
;                     const LAS unsigned char* a0 = Vu + (vb0l ^ (64 * t)); const LAS unsigned char* a1 = Vu + (vb1l ^ (64 * t));
;                     const bf16x8 v0 = tr_pair(a0, a1), v1 = tr_pair(a0 + 4096, a1 + 4096);
;                     O[0][t] = __builtin_amdgcn_mfma_f32_32x32x16_bf16(v0, P[0][0], O[0][t], 0, 0, 0);
;                     O[1][t] = __builtin_amdgcn_mfma_f32_32x32x16_bf16(v0, P[1][0], O[1][t], 0, 0, 0);
;                     O[0][t] = __builtin_amdgcn_mfma_f32_32x32x16_bf16(v1, P[0][1], O[0][t], 0, 0, 0);
.Lfb_loopF:
	s_waitcnt lgkmcnt(3)
	v_mfma_f32_32x32x16_bf16 v[146:161], v[198:201], v[166:169], 0
	v_exp_f32_e32 v138, v138
	v_exp_f32_e32 v139, v139
	v_exp_f32_e32 v140, v140
	v_exp_f32_e32 v141, v141
	s_waitcnt lgkmcnt(2)
	v_mfma_f32_32x32x16_bf16 v[146:161], v[202:205], v[170:173], v[146:161]
	v_add_f32_e32 v212, v212, v138
	v_add_f32_e32 v212, v212, v139
	v_add_f32_e32 v212, v212, v140
	v_add_f32_e32 v212, v212, v141
	v_exp_f32_e32 v142, v142
	v_exp_f32_e32 v143, v143
	s_waitcnt lgkmcnt(1)
	v_mfma_f32_32x32x16_bf16 v[146:161], v[208:211], v[174:177], v[146:161]
	v_exp_f32_e32 v144, v144
	v_exp_f32_e32 v145, v145
	v_add_f32_e32 v212, v212, v142
	v_add_f32_e32 v212, v212, v143
	s_waitcnt lgkmcnt(0)
	v_mfma_f32_32x32x16_bf16 v[146:161], v[230:233], v[178:181], v[146:161]
	v_add_f32_e32 v212, v212, v144
	v_add_f32_e32 v212, v212, v145
	v_cvt_pk_bf16_f32 v226, v138, v139
	v_cvt_pk_bf16_f32 v227, v140, v141
	v_cvt_pk_bf16_f32 v228, v142, v143
	v_cvt_pk_bf16_f32 v229, v144, v145
	v_mfma_f32_32x32x16_bf16 v[130:145], v[198:201], v[182:185], 0
	ds_read_b64_tr_b16 v[198:199], v234 offset:16384
	ds_read_b64_tr_b16 v[200:201], v235 offset:16384
	v_mfma_f32_32x32x16_bf16 v[130:145], v[202:205], v[186:189], v[130:145]
	ds_read_b64_tr_b16 v[202:203], v237 offset:16384
	ds_read_b64_tr_b16 v[204:205], v236 offset:16384
	v_exp_f32_e32 v146, v146
	v_exp_f32_e32 v147, v147
	v_exp_f32_e32 v148, v148
	v_mfma_f32_32x32x16_bf16 v[130:145], v[208:211], v[190:193], v[130:145]
	ds_read_b64_tr_b16 v[208:209], v238 offset:16384
	ds_read_b64_tr_b16 v[210:211], v239 offset:16384
	v_exp_f32_e32 v149, v149
	v_add_f32_e32 v213, v213, v146
	v_add_f32_e32 v213, v213, v147
	v_add_f32_e32 v213, v213, v148
	v_mfma_f32_32x32x16_bf16 v[130:145], v[230:233], v[194:197], v[130:145]
	ds_read_b64_tr_b16 v[230:231], v250 offset:16384
	ds_read_b64_tr_b16 v[232:233], v251 offset:16384
	v_add_f32_e32 v213, v213, v149
	v_exp_f32_e32 v150, v150
	v_exp_f32_e32 v151, v151
	s_waitcnt lgkmcnt(6)
	v_mfma_f32_32x32x16_bf16 v[114:129], v[198:201], v[214:217], v[114:129]
	v_exp_f32_e32 v152, v152
	v_exp_f32_e32 v153, v153
	v_mfma_f32_32x32x16_bf16 v[50:65], v[198:201], v[218:221], v[50:65]
	ds_read_b64_tr_b16 v[198:199], v234 offset:20480
	ds_read_b64_tr_b16 v[200:201], v235 offset:20480
	v_add_f32_e32 v213, v213, v150
	v_add_f32_e32 v213, v213, v151
	v_add_f32_e32 v213, v213, v152
	v_add_f32_e32 v213, v213, v153
	s_waitcnt lgkmcnt(6)
	v_mfma_f32_32x32x16_bf16 v[98:113], v[202:205], v[214:217], v[98:113]
	v_exp_f32_e32 v154, v154
	v_exp_f32_e32 v155, v155
	v_mfma_f32_32x32x16_bf16 v[34:49], v[202:205], v[218:221], v[34:49]
	ds_read_b64_tr_b16 v[202:203], v237 offset:20480
	ds_read_b64_tr_b16 v[204:205], v236 offset:20480
	v_exp_f32_e32 v156, v156
	v_exp_f32_e32 v157, v157
	s_waitcnt lgkmcnt(6)
	v_mfma_f32_32x32x16_bf16 v[82:97], v[208:211], v[214:217], v[82:97]
	v_add_f32_e32 v213, v213, v154
	v_add_f32_e32 v213, v213, v155
	v_add_f32_e32 v213, v213, v156
	v_add_f32_e32 v213, v213, v157
	v_mfma_f32_32x32x16_bf16 v[18:33], v[208:211], v[218:221], v[18:33]
	ds_read_b64_tr_b16 v[208:209], v238 offset:20480
	ds_read_b64_tr_b16 v[210:211], v239 offset:20480
	v_exp_f32_e32 v158, v158
	v_exp_f32_e32 v159, v159
	s_waitcnt lgkmcnt(6)
	v_mfma_f32_32x32x16_bf16 v[66:81], v[230:233], v[214:217], v[66:81]
	v_exp_f32_e32 v160, v160
	v_exp_f32_e32 v161, v161
	v_mfma_f32_32x32x16_bf16 v[2:17], v[230:233], v[218:221], v[2:17]
	ds_read_b64_tr_b16 v[230:231], v250 offset:20480
	ds_read_b64_tr_b16 v[232:233], v251 offset:20480
	v_add_f32_e32 v213, v213, v158
	v_add_f32_e32 v213, v213, v159
	v_add_f32_e32 v213, v213, v160
	v_add_f32_e32 v213, v213, v161
	s_cmpk_eq_u32 s29, 0x7f
	s_cbranch_scc1 .Lfb_last0F
	s_add_i32 s2, s29, 1
	s_and_b32 s2, s2, 3
	s_mov_b32 s37, 0x8000
	s_cmp_eq_u32 s2, 0
	s_cselect_b32 s37, 0xfffe8000, s37
	v_add_u32_e32 v1, s37, v1
	s_add_i32 s2, s29, 3
	s_lshl_b32 s10, s2, 6
	s_add_u32 s10, s26, s10
	s_addc_u32 s11, s27, 0
	s_lshl_b64 s[10:11], s[10:11], 13
	s_add_u32 s42, s25, s10
	s_addc_u32 s43, s28, s11
	s_add_u32 s10, s22, s10
	s_addc_u32 s11, s23, s11
	s_and_b32 s2, s2, 3
	s_lshl_b32 s2, s2, 15
	s_add_i32 s2, s2, s34
	s_cmpk_eq_u32 s29, 0x7e
	s_cbranch_scc1 .Lfb_w0F
	s_waitcnt vmcnt(4)
.Lfb_w1F:
	s_barrier
	s_waitcnt lgkmcnt(6)
	v_mfma_f32_32x32x16_bf16 v[114:129], v[198:201], v[222:225], v[114:129]
	v_exp_f32_e32 v130, v130
	v_exp_f32_e32 v131, v131
	v_mfma_f32_32x32x16_bf16 v[50:65], v[198:201], v[226:229], v[50:65]
	v_add_u32_e32 v198, v246, v1
	ds_read_b128 v[198:201], v198
	v_exp_f32_e32 v132, v132
	v_exp_f32_e32 v133, v133
	s_cmpk_gt_u32 s29, 0x7c
	s_cbranch_scc1 .Lfb_nd0F
	s_mov_b32 m0, s2
	s_nop 0
	global_load_lds_dwordx4 v241, s[42:43]

; __device__ __forceinline__ void diff_attn_phase(const Params& p, LAS unsigned char* lds) {
;     ...
;             if (ch + 1 < NCH) asm volatile("s_waitcnt vmcnt(4)" ::: "memory"); else asm volatile("s_waitcnt vmcnt(0)" ::: "memory");
.Lfb_w0F:
	s_waitcnt vmcnt(0)
	s_branch .Lfb_w1F
